# static priority raise (s_setprio 1) for the second-dispatched wave half during the attention units, reset before gMLP
# speedup vs baseline: 1.0026x; 1.0000x over previous
.LBB0_35:
	s_mov_b32 s44, 0
	s_add_i32 s2, s44, s76
	s_waitcnt vmcnt(0)
	v_mbcnt_lo_u32_b32 v0, -1, 0
	v_mbcnt_hi_u32_b32 v0, -1, v0
	s_add_i32 s18, s44, s69
	v_lshl_add_u32 v176, s2, 6, v0
	s_add_i32 s82, s44, s72
	v_readfirstlane_b32 s2, v176
	s_ashr_i32 s6, s2, 6
	v_readlane_b32 s4, v254, 11
	s_cmp_gt_u32 s4, 16
	s_cselect_b64 s[2:3], -1, 0
	s_cmp_lt_u32 s4, 17
	s_cselect_b64 s[10:11], -1, 0
	s_and_b64 s[4:5], s[10:11], exec
	s_mov_b32 s4, 0x12000
	s_cselect_b32 s4, s4, 0x10000
	s_lshl_b32 s5, s82, 3
	s_abs_i32 s7, s5
	v_cvt_f32_u32_e32 v1, s7
	s_mov_b32 s14, s18
	v_writelane_b32 v254, s14, 41
	s_lshl_b32 s13, s18, 3
	v_rcp_iflag_f32_e32 v1, v1
	v_writelane_b32 v254, s15, 42
	s_add_i32 s6, s6, s13
	s_sub_i32 s13, 0, s7
	v_mul_f32_e32 v1, 0x4f7ffffe, v1
	v_cvt_u32_f32_e32 v1, v1
	s_add_i32 s12, s4, s5
	s_add_i32 s12, s12, -1
	s_xor_b32 s5, s12, s5
	v_readfirstlane_b32 s14, v1
	s_mul_i32 s13, s13, s14
	s_mul_hi_u32 s13, s14, s13
	s_abs_i32 s12, s12
	s_add_i32 s14, s14, s13
	s_mul_hi_u32 s13, s12, s14
	s_mul_i32 s14, s13, s7
	s_sub_i32 s12, s12, s14
	s_ashr_i32 s5, s5, 31
	s_add_i32 s14, s13, 1
	s_sub_i32 s15, s12, s7
	s_cmp_ge_u32 s12, s7
	s_cselect_b32 s13, s14, s13
	s_cselect_b32 s12, s15, s12
	s_add_i32 s14, s13, 1
	s_cmp_ge_u32 s12, s7
	s_cselect_b32 s7, s14, s13
	s_xor_b32 s7, s7, s5
	s_sub_i32 s5, s7, s5
	s_mul_i32 s56, s5, s6
	s_add_i32 s5, s56, s5
	s_min_i32 s57, s5, s4
	s_cmp_ge_i32 s56, s57
	s_mov_b32 s54, 0x800000
	s_cbranch_scc1 .LBB0_134
	v_readlane_b32 s28, v254, 11
	s_cmp_lg_u32 s28, 21
	s_cselect_b64 s[6:7], -1, 0
	s_cmp_eq_u32 s28, 21
	s_cselect_b64 s[12:13], -1, 0
	s_cmp_eq_u32 s28, 17
	s_cselect_b64 s[14:15], -1, 0
	s_lshl_b64 s[4:5], s[44:45], 3
	s_add_u32 s22, s70, s4
	v_readlane_b32 s24, v253, 62
	s_addc_u32 s23, s71, s5
	v_readlane_b32 s26, v254, 0
	v_readlane_b32 s27, v254, 1
	s_add_u32 s4, s26, s44
	s_addc_u32 s5, s27, 0
	s_lshl_b64 s[18:19], s[44:45], 2
	v_readlane_b32 s25, v253, 63
	s_add_u32 s58, s24, s18
	s_addc_u32 s59, s25, s19
	s_cmp_eq_u32 s28, 10
	s_cselect_b64 s[18:19], -1, 0
	s_and_b64 s[20:21], s[18:19], exec
	s_movk_i32 s20, 0x400
	s_cselect_b32 s60, s20, 0x1000
	s_cselect_b32 s61, 0, 0xc00
	s_or_b64 s[12:13], s[18:19], s[12:13]
	s_and_b64 s[18:19], s[12:13], exec
	s_cselect_b32 s18, 64, 48
	s_add_u32 s18, s22, s18
	s_addc_u32 s19, s23, 0
	s_load_dwordx2 s[18:19], s[18:19], 0x0
	s_and_b64 s[10:11], s[10:11], exec
	s_cselect_b32 s20, 0, 0x1000
	v_and_b32_e32 v34, 63, v0
	v_lshlrev_b32_e32 v192, 5, v34
	s_waitcnt lgkmcnt(0)
	s_add_u32 s10, s18, s20
	s_addc_u32 s11, s19, 0
	s_and_b64 s[12:13], s[12:13], exec
	s_cselect_b32 s12, 0x48, 56
	s_add_u32 s12, s22, s12
	s_addc_u32 s13, s23, 0
	s_load_dwordx2 s[12:13], s[12:13], 0x0
	v_xor_b32_e32 v32, 1, v229
	v_cmp_lt_i32_e32 vcc, v32, v231
	v_mov_b32_e32 v33, v193
	v_mov_b32_e32 v62, 0
	s_waitcnt lgkmcnt(0)
	s_add_u32 s12, s12, s20
	s_addc_u32 s13, s13, 0
	global_load_dwordx4 v[0:3], v192, s[10:11] offset:16
	global_load_dwordx4 v[4:7], v192, s[10:11]
	global_load_dwordx4 v[8:11], v192, s[12:13] offset:16
	global_load_dwordx4 v[12:15], v192, s[12:13]
	global_load_dwordx4 v[16:19], v192, s[10:11] offset:2064
	global_load_dwordx4 v[20:23], v192, s[10:11] offset:2048
	global_load_dwordx4 v[24:27], v192, s[12:13] offset:2064
	global_load_dwordx4 v[28:31], v192, s[12:13] offset:2048
	v_cndmask_b32_e32 v32, v229, v32, vcc
	v_lshlrev_b32_e32 v109, 2, v32
	v_xor_b32_e32 v32, 2, v229
	v_cmp_lt_i32_e32 vcc, v32, v231
	s_cmp_eq_u32 s28, 6
	s_cselect_b64 s[10:11], -1, 0
	v_cndmask_b32_e32 v32, v229, v32, vcc
	v_lshlrev_b32_e32 v121, 2, v32
	v_xor_b32_e32 v32, 4, v229
	v_cmp_lt_i32_e32 vcc, v32, v231
	s_and_b64 s[12:13], s[10:11], exec
	s_mov_b32 s12, 0x44d4000
	v_cndmask_b32_e32 v32, v229, v32, vcc
	v_lshlrev_b32_e32 v122, 2, v32
	v_xor_b32_e32 v32, 8, v229
	v_cmp_lt_i32_e32 vcc, v32, v231
	s_cselect_b32 s12, s12, 0x459a000
	s_or_b64 s[10:11], s[10:11], s[14:15]
	v_cndmask_b32_e32 v32, v229, v32, vcc
	v_lshlrev_b32_e32 v123, 2, v32
	v_xor_b32_e32 v32, 16, v229
	v_cmp_lt_i32_e32 vcc, v32, v231
	s_add_u32 s62, s4, 0x38260000
	s_addc_u32 s63, s5, 0
	v_cndmask_b32_e32 v32, v229, v32, vcc
	v_lshlrev_b32_e32 v124, 2, v32
	v_xor_b32_e32 v32, 32, v229
	s_add_u32 s64, s4, 0x3d2e4000
	v_cmp_lt_i32_e32 vcc, v32, v231
	s_addc_u32 s65, s5, 0
	s_add_u32 s14, s4, s12
	v_cndmask_b32_e32 v32, v229, v32, vcc
	v_lshlrev_b32_e32 v125, 2, v32
	v_lshlrev_b32_e32 v32, 4, v34
	s_addc_u32 s15, s5, 0
	v_lshl_add_u64 v[32:33], s[4:5], 0, v[32:33]
	s_mov_b64 s[4:5], 0x4660000
	v_lshl_add_u64 v[110:111], v[32:33], 0, s[4:5]
	v_cmp_eq_u32_e32 vcc, 0, v34
	s_mov_b64 s[4:5], 0x16660000
	v_lshlrev_b32_e32 v108, 3, v34
	s_mov_b32 s68, -1
	s_and_b64 s[12:13], s[6:7], vcc
	v_lshl_add_u64 v[112:113], s[14:15], 0, v[192:193]
	v_lshl_add_u64 v[114:115], v[32:33], 0, s[4:5]
	v_mov_b32_e32 v63, v62
	v_mov_b32_e32 v54, v62
	v_mov_b32_e32 v55, v62
	v_mov_b32_e32 v60, v62
	v_mov_b32_e32 v61, v62
	v_mov_b32_e32 v52, v62
	v_mov_b32_e32 v53, v62
	v_mov_b32_e32 v58, v62
	v_mov_b32_e32 v59, v62
	v_mov_b32_e32 v50, v62
	v_mov_b32_e32 v51, v62
	v_mov_b32_e32 v56, v62
	v_mov_b32_e32 v57, v62
	v_mov_b32_e32 v48, v62
	v_mov_b32_e32 v49, v62
	v_mov_b32_e32 v38, v62
	v_mov_b32_e32 v39, v62
	v_mov_b32_e32 v46, v62
	v_mov_b32_e32 v47, v62
	v_mov_b32_e32 v36, v62
	v_mov_b32_e32 v37, v62
	v_mov_b32_e32 v44, v62
	v_mov_b32_e32 v45, v62
	v_mov_b32_e32 v34, v62
	v_mov_b32_e32 v35, v62
	v_mov_b32_e32 v42, v62
	v_mov_b32_e32 v43, v62
	v_mov_b32_e32 v32, v62
	v_mov_b32_e32 v33, v62
	v_mov_b32_e32 v40, v62
	v_mov_b32_e32 v41, v62
	s_branch .LBB0_38
	s_nop 0
	s_nop 0
	s_nop 0
	s_nop 0
	s_nop 0
	s_nop 0
	s_nop 0
	s_nop 0
	s_nop 0
	s_nop 0
	s_nop 0
	s_nop 0
	s_nop 0
.LBB0_37:
	s_add_i32 s56, s56, 4
	s_cmp_ge_i32 s56, s57
	s_cbranch_scc1 .LBB0_134

.LBB0_329:
	v_readlane_b32 s0, v254, 11
	s_cmp_eq_u32 s0, 4
	s_cbranch_scc0 .LBB0_357
	v_readlane_b32 s4, v253, 62
	s_mov_b32 s2, 0
	s_add_i32 s0, s2, s76
	v_readlane_b32 s6, v254, 0
	v_readlane_b32 s7, v254, 1
	s_add_u32 s26, s6, s2
	s_addc_u32 s27, s7, 0
	s_add_i32 s6, s2, s69
	s_add_i32 s82, s2, s72
	s_waitcnt vmcnt(0)
	v_mbcnt_lo_u32_b32 v0, -1, 0
	v_mbcnt_hi_u32_b32 v0, -1, v0
	v_readlane_b32 s5, v253, 63
	v_lshl_add_u32 v176, s0, 6, v0
	s_add_u32 s0, s26, 0x1f660000
	s_addc_u32 s1, s27, 0
	s_add_u32 s10, s26, 0x16660000
	s_mov_b32 s4, s6
	s_addc_u32 s11, s27, 0
	v_writelane_b32 v254, s4, 41
	s_cmpk_gt_i32 s6, 0x47f
	s_mov_b32 s3, s45
	v_writelane_b32 v254, s5, 42
	s_cbranch_scc1 .LBB0_358
	v_readlane_b32 s4, v254, 41
	s_and_b32 s28, s4, 7
	s_lshr_b32 s29, s4, 3
	s_ashr_i32 s30, s4, 6
	s_cmpk_eq_i32 s82, 0x100
	s_mov_b32 s31, 0
	s_cselect_b64 s[12:13], -1, 0
	s_mov_b32 s14, s4
	v_readlane_b32 s5, v254, 42
	s_cmp_gt_u32 s76, 3
	s_cbranch_scc0 .Lattn_prio_skip
	s_setprio 1
.Lattn_prio_skip:
	s_branch .LBB0_333
.LBB0_332:
	s_or_b64 exec, exec, s[6:7]
	s_waitcnt lgkmcnt(0)
	s_lshl_b64 s[4:5], s[14:15], 11
	v_ashrrev_i32_e32 v64, 5, v177
	v_lshl_add_u32 v67, v64, 4, v179
	ds_read2_b32 v[70:71], v67 offset1:1
	ds_read2_b32 v[72:73], v67 offset0:2 offset1:3
	ds_read2_b32 v[74:75], v67 offset0:8 offset1:9
	ds_read2_b32 v[76:77], v67 offset0:10 offset1:11
	ds_read2_b32 v[78:79], v67 offset0:16 offset1:17
	ds_read2_b32 v[80:81], v67 offset0:18 offset1:19
	ds_read2_b32 v[82:83], v67 offset0:24 offset1:25
	ds_read2_b32 v[84:85], v67 offset0:26 offset1:27
	s_add_u32 s4, s10, s4
	s_addc_u32 s5, s11, s5
	s_add_u32 s4, s4, s18
	s_addc_u32 s5, s5, s19
	s_add_i32 s31, s31, 1
	v_readlane_b32 s6, v254, 41
	v_readlane_b32 s7, v254, 42
	v_and_b32_e32 v65, 31, v177
	v_lshlrev_b32_e32 v66, 8, v178
	v_lshl_add_u32 v66, v64, 10, v66
	v_lshl_add_u32 v66, v65, 1, v66
	v_add_u32_e32 v66, 0x11000, v66
	s_waitcnt lgkmcnt(0)
	v_rcp_f32_e32 v70, v70
	v_rcp_f32_e32 v71, v71
	v_rcp_f32_e32 v72, v72
	v_rcp_f32_e32 v73, v73
	v_rcp_f32_e32 v74, v74
	v_rcp_f32_e32 v75, v75
	v_rcp_f32_e32 v76, v76
	v_rcp_f32_e32 v77, v77
	v_rcp_f32_e32 v78, v78
	v_rcp_f32_e32 v79, v79
	v_rcp_f32_e32 v80, v80
	v_rcp_f32_e32 v81, v81
	v_rcp_f32_e32 v82, v82
	v_rcp_f32_e32 v83, v83
	v_rcp_f32_e32 v84, v84
	v_rcp_f32_e32 v85, v85
	s_nop 1
	v_mul_f32_e32 v0, v0, v70
	v_cvt_pk_bf16_f32 v0, v0, v193
	ds_write_b16 v66, v0 offset:0
	v_mul_f32_e32 v48, v48, v70
	v_cvt_pk_bf16_f32 v48, v48, v193
	ds_write_b16 v66, v48 offset:64
	v_mul_f32_e32 v32, v32, v70
	v_cvt_pk_bf16_f32 v32, v32, v193
	ds_write_b16 v66, v32 offset:128
	v_mul_f32_e32 v16, v16, v70
	v_cvt_pk_bf16_f32 v16, v16, v193
	ds_write_b16 v66, v16 offset:192
	v_mul_f32_e32 v1, v1, v71
	v_cvt_pk_bf16_f32 v1, v1, v193
	ds_write_b16 v66, v1 offset:256
	v_mul_f32_e32 v49, v49, v71
	v_cvt_pk_bf16_f32 v49, v49, v193
	ds_write_b16 v66, v49 offset:320
	v_mul_f32_e32 v33, v33, v71
	v_cvt_pk_bf16_f32 v33, v33, v193
	ds_write_b16 v66, v33 offset:384
	v_mul_f32_e32 v17, v17, v71
	v_cvt_pk_bf16_f32 v17, v17, v193
	ds_write_b16 v66, v17 offset:448
	s_waitcnt lgkmcnt(7)
	v_mul_f32_e32 v2, v2, v72
	v_cvt_pk_bf16_f32 v2, v2, v193
	ds_write_b16 v66, v2 offset:512
	v_mul_f32_e32 v50, v50, v72
	v_cvt_pk_bf16_f32 v50, v50, v193
	ds_write_b16 v66, v50 offset:576
	v_mul_f32_e32 v34, v34, v72
	v_cvt_pk_bf16_f32 v34, v34, v193
	ds_write_b16 v66, v34 offset:640
	v_mul_f32_e32 v18, v18, v72
	v_cvt_pk_bf16_f32 v18, v18, v193
	ds_write_b16 v66, v18 offset:704
	v_mul_f32_e32 v3, v3, v73
	v_cvt_pk_bf16_f32 v3, v3, v193
	ds_write_b16 v66, v3 offset:768
	v_mul_f32_e32 v51, v51, v73
	v_cvt_pk_bf16_f32 v51, v51, v193
	ds_write_b16 v66, v51 offset:832
	v_mul_f32_e32 v35, v35, v73
	v_cvt_pk_bf16_f32 v35, v35, v193
	ds_write_b16 v66, v35 offset:896
	v_mul_f32_e32 v19, v19, v73
	v_cvt_pk_bf16_f32 v19, v19, v193
	ds_write_b16 v66, v19 offset:960
	s_waitcnt lgkmcnt(7)
	v_mul_f32_e32 v4, v4, v74
	v_cvt_pk_bf16_f32 v4, v4, v193
	ds_write_b16 v66, v4 offset:2048
	v_mul_f32_e32 v52, v52, v74
	v_cvt_pk_bf16_f32 v52, v52, v193
	ds_write_b16 v66, v52 offset:2112
	v_mul_f32_e32 v36, v36, v74
	v_cvt_pk_bf16_f32 v36, v36, v193
	ds_write_b16 v66, v36 offset:2176
	v_mul_f32_e32 v20, v20, v74
	v_cvt_pk_bf16_f32 v20, v20, v193
	ds_write_b16 v66, v20 offset:2240
	v_mul_f32_e32 v5, v5, v75
	v_cvt_pk_bf16_f32 v5, v5, v193
	ds_write_b16 v66, v5 offset:2304
	v_mul_f32_e32 v53, v53, v75
	v_cvt_pk_bf16_f32 v53, v53, v193
	ds_write_b16 v66, v53 offset:2368
	v_mul_f32_e32 v37, v37, v75
	v_cvt_pk_bf16_f32 v37, v37, v193
	ds_write_b16 v66, v37 offset:2432
	v_mul_f32_e32 v21, v21, v75
	v_cvt_pk_bf16_f32 v21, v21, v193
	ds_write_b16 v66, v21 offset:2496
	s_waitcnt lgkmcnt(7)
	v_mul_f32_e32 v6, v6, v76
	v_cvt_pk_bf16_f32 v6, v6, v193
	ds_write_b16 v66, v6 offset:2560
	v_mul_f32_e32 v54, v54, v76
	v_cvt_pk_bf16_f32 v54, v54, v193
	ds_write_b16 v66, v54 offset:2624
	v_mul_f32_e32 v38, v38, v76
	v_cvt_pk_bf16_f32 v38, v38, v193
	ds_write_b16 v66, v38 offset:2688
	v_mul_f32_e32 v22, v22, v76
	v_cvt_pk_bf16_f32 v22, v22, v193
	ds_write_b16 v66, v22 offset:2752
	v_mul_f32_e32 v7, v7, v77
	v_cvt_pk_bf16_f32 v7, v7, v193
	ds_write_b16 v66, v7 offset:2816
	v_mul_f32_e32 v55, v55, v77
	v_cvt_pk_bf16_f32 v55, v55, v193
	ds_write_b16 v66, v55 offset:2880
	v_mul_f32_e32 v39, v39, v77
	v_cvt_pk_bf16_f32 v39, v39, v193
	ds_write_b16 v66, v39 offset:2944
	v_mul_f32_e32 v23, v23, v77
	v_cvt_pk_bf16_f32 v23, v23, v193
	ds_write_b16 v66, v23 offset:3008
	s_waitcnt lgkmcnt(7)
	v_mul_f32_e32 v8, v8, v78
	v_cvt_pk_bf16_f32 v8, v8, v193
	ds_write_b16 v66, v8 offset:4096
	v_mul_f32_e32 v56, v56, v78
	v_cvt_pk_bf16_f32 v56, v56, v193
	ds_write_b16 v66, v56 offset:4160
	v_mul_f32_e32 v40, v40, v78
	v_cvt_pk_bf16_f32 v40, v40, v193
	ds_write_b16 v66, v40 offset:4224
	v_mul_f32_e32 v24, v24, v78
	v_cvt_pk_bf16_f32 v24, v24, v193
	ds_write_b16 v66, v24 offset:4288
	v_mul_f32_e32 v9, v9, v79
	v_cvt_pk_bf16_f32 v9, v9, v193
	ds_write_b16 v66, v9 offset:4352
	v_mul_f32_e32 v57, v57, v79
	v_cvt_pk_bf16_f32 v57, v57, v193
	ds_write_b16 v66, v57 offset:4416
	v_mul_f32_e32 v41, v41, v79
	v_cvt_pk_bf16_f32 v41, v41, v193
	ds_write_b16 v66, v41 offset:4480
	v_mul_f32_e32 v25, v25, v79
	v_cvt_pk_bf16_f32 v25, v25, v193
	ds_write_b16 v66, v25 offset:4544
	s_waitcnt lgkmcnt(7)
	v_mul_f32_e32 v10, v10, v80
	v_cvt_pk_bf16_f32 v10, v10, v193
	ds_write_b16 v66, v10 offset:4608
	v_mul_f32_e32 v58, v58, v80
	v_cvt_pk_bf16_f32 v58, v58, v193
	ds_write_b16 v66, v58 offset:4672
	v_mul_f32_e32 v42, v42, v80
	v_cvt_pk_bf16_f32 v42, v42, v193
	ds_write_b16 v66, v42 offset:4736
	v_mul_f32_e32 v26, v26, v80
	v_cvt_pk_bf16_f32 v26, v26, v193
	ds_write_b16 v66, v26 offset:4800
	v_mul_f32_e32 v11, v11, v81
	v_cvt_pk_bf16_f32 v11, v11, v193
	ds_write_b16 v66, v11 offset:4864
	v_mul_f32_e32 v59, v59, v81
	v_cvt_pk_bf16_f32 v59, v59, v193
	ds_write_b16 v66, v59 offset:4928
	v_mul_f32_e32 v43, v43, v81
	v_cvt_pk_bf16_f32 v43, v43, v193
	ds_write_b16 v66, v43 offset:4992
	v_mul_f32_e32 v27, v27, v81
	v_cvt_pk_bf16_f32 v27, v27, v193
	ds_write_b16 v66, v27 offset:5056
	s_waitcnt lgkmcnt(7)
	v_mul_f32_e32 v12, v12, v82
	v_cvt_pk_bf16_f32 v12, v12, v193
	ds_write_b16 v66, v12 offset:6144
	v_mul_f32_e32 v60, v60, v82
	v_cvt_pk_bf16_f32 v60, v60, v193
	ds_write_b16 v66, v60 offset:6208
	v_mul_f32_e32 v44, v44, v82
	v_cvt_pk_bf16_f32 v44, v44, v193
	ds_write_b16 v66, v44 offset:6272
	v_mul_f32_e32 v28, v28, v82
	v_cvt_pk_bf16_f32 v28, v28, v193
	ds_write_b16 v66, v28 offset:6336
	v_mul_f32_e32 v13, v13, v83
	v_cvt_pk_bf16_f32 v13, v13, v193
	ds_write_b16 v66, v13 offset:6400
	v_mul_f32_e32 v61, v61, v83
	v_cvt_pk_bf16_f32 v61, v61, v193
	ds_write_b16 v66, v61 offset:6464
	v_mul_f32_e32 v45, v45, v83
	v_cvt_pk_bf16_f32 v45, v45, v193
	ds_write_b16 v66, v45 offset:6528
	v_mul_f32_e32 v29, v29, v83
	v_cvt_pk_bf16_f32 v29, v29, v193
	ds_write_b16 v66, v29 offset:6592
	s_waitcnt lgkmcnt(7)
	v_mul_f32_e32 v14, v14, v84
	v_cvt_pk_bf16_f32 v14, v14, v193
	ds_write_b16 v66, v14 offset:6656
	v_mul_f32_e32 v62, v62, v84
	v_cvt_pk_bf16_f32 v62, v62, v193
	ds_write_b16 v66, v62 offset:6720
	v_mul_f32_e32 v46, v46, v84
	v_cvt_pk_bf16_f32 v46, v46, v193
	ds_write_b16 v66, v46 offset:6784
	v_mul_f32_e32 v30, v30, v84
	v_cvt_pk_bf16_f32 v30, v30, v193
	ds_write_b16 v66, v30 offset:6848
	v_mul_f32_e32 v15, v15, v85
	v_cvt_pk_bf16_f32 v15, v15, v193
	ds_write_b16 v66, v15 offset:6912
	v_mul_f32_e32 v63, v63, v85
	v_cvt_pk_bf16_f32 v63, v63, v193
	ds_write_b16 v66, v63 offset:6976
	v_mul_f32_e32 v47, v47, v85
	v_cvt_pk_bf16_f32 v47, v47, v193
	ds_write_b16 v66, v47 offset:7040
	v_mul_f32_e32 v31, v31, v85
	v_cvt_pk_bf16_f32 v31, v31, v193
	ds_write_b16 v66, v31 offset:7104
	v_lshrrev_b32_e32 v64, 4, v177
	v_and_b32_e32 v65, 15, v177
	v_lshlrev_b32_e32 v66, 8, v178
	v_lshl_add_u32 v66, v64, 8, v66
	v_lshl_add_u32 v66, v65, 4, v66
	v_add_u32_e32 v66, 0x11000, v66
	v_add_u32_e32 v68, v178, v64
	v_mov_b32_e32 v69, 0
	v_lshlrev_b64 v[68:69], 11, v[68:69]
	v_lshl_add_u64 v[68:69], s[4:5], 0, v[68:69]
	v_lshlrev_b32_e32 v70, 4, v65
	v_mov_b32_e32 v71, 0
	v_lshl_add_u64 v[68:69], v[68:69], 0, v[70:71]
	s_waitcnt lgkmcnt(0)
	ds_read_b128 v[0:3], v66 offset:0
	ds_read_b128 v[4:7], v66 offset:1024
	ds_read_b128 v[8:11], v66 offset:2048
	ds_read_b128 v[12:15], v66 offset:3072
	ds_read_b128 v[16:19], v66 offset:4096
	ds_read_b128 v[20:23], v66 offset:5120
	ds_read_b128 v[24:27], v66 offset:6144
	ds_read_b128 v[28:31], v66 offset:7168
	s_waitcnt lgkmcnt(7)
	global_store_dwordx4 v[68:69], v[0:3], off offset:1024
	v_add_co_u32_e32 v68, vcc, 0x2000, v68
	s_nop 1
	v_addc_co_u32_e32 v69, vcc, 0, v69, vcc
	s_waitcnt lgkmcnt(6)
	global_store_dwordx4 v[68:69], v[4:7], off offset:1024
	v_add_co_u32_e32 v68, vcc, 0x2000, v68
	s_nop 1
	v_addc_co_u32_e32 v69, vcc, 0, v69, vcc
	s_waitcnt lgkmcnt(5)
	global_store_dwordx4 v[68:69], v[8:11], off offset:1024
	v_add_co_u32_e32 v68, vcc, 0x2000, v68
	s_nop 1
	v_addc_co_u32_e32 v69, vcc, 0, v69, vcc
	s_waitcnt lgkmcnt(4)
	global_store_dwordx4 v[68:69], v[12:15], off offset:1024
	v_add_co_u32_e32 v68, vcc, 0x2000, v68
	s_nop 1
	v_addc_co_u32_e32 v69, vcc, 0, v69, vcc
	s_waitcnt lgkmcnt(3)
	global_store_dwordx4 v[68:69], v[16:19], off offset:1024
	v_add_co_u32_e32 v68, vcc, 0x2000, v68
	s_nop 1
	v_addc_co_u32_e32 v69, vcc, 0, v69, vcc
	s_waitcnt lgkmcnt(2)
	global_store_dwordx4 v[68:69], v[20:23], off offset:1024
	v_add_co_u32_e32 v68, vcc, 0x2000, v68
	s_nop 1
	v_addc_co_u32_e32 v69, vcc, 0, v69, vcc
	s_waitcnt lgkmcnt(1)
	global_store_dwordx4 v[68:69], v[24:27], off offset:1024
	v_add_co_u32_e32 v68, vcc, 0x2000, v68
	s_nop 1
	v_addc_co_u32_e32 v69, vcc, 0, v69, vcc
	s_waitcnt lgkmcnt(0)
	global_store_dwordx4 v[68:69], v[28:31], off offset:1024
	s_branch .Lattn_epi_pad_end
	s_nop 0
	s_nop 0
	s_nop 0
	s_nop 0
	s_nop 0
	s_nop 0
	s_nop 0
	s_nop 0
	s_nop 0
	s_nop 0
	s_nop 0
	s_nop 0
	s_nop 0
	s_nop 0
	s_nop 0
	s_nop 0
	s_nop 0
	s_nop 0
	s_nop 0
	s_nop 0
	s_nop 0
	s_nop 0
	s_nop 0

.LBB0_358:
	s_setprio 0
	v_readlane_b32 s4, v254, 41
	s_waitcnt vmcnt(63) expcnt(7) lgkmcnt(15)
	s_barrier
	s_cmpk_gt_i32 s4, 0x8ff
	v_readfirstlane_b32 s4, v176
	v_readlane_b32 s5, v254, 42
	s_cbranch_scc1 .LBB0_361
	s_add_u32 s12, s26, 0x3e80000
	s_addc_u32 s13, s27, 0
	s_lshl_b64 s[2:3], s[2:3], 3
	s_add_u32 s2, s70, s2
	v_and_b32_e32 v1, 15, v176
	s_addc_u32 s3, s71, s3
	s_ashr_i32 s4, s4, 6
	s_waitcnt vmcnt(5)
	v_lshlrev_b32_e32 v8, 8, v1
	v_lshlrev_b32_e32 v3, 4, v176
	v_lshl_or_b32 v0, s4, 12, v8
	v_and_b32_e32 v2, 48, v176
	v_and_b32_e32 v4, 0x70, v3
	s_waitcnt vmcnt(3)
	v_lshl_or_b32 v16, s4, 4, v1
	s_movk_i32 s4, 0x80
	v_bitop3_b32 v41, v2, v4, s4 bitop3:0x36
	s_movk_i32 s4, 0xc0
	v_bitop3_b32 v19, v3, v2, s33 bitop3:0x6c
	v_bitop3_b32 v35, v2, v4, 64 bitop3:0x36
	v_bitop3_b32 v43, v2, v4, s4 bitop3:0x36
	v_lshlrev_b32_e32 v2, 4, v1
	v_bitop3_b32 v64, v2, v176, s33 bitop3:0x78
	v_add_u32_e32 v2, 0x200, v176
	s_waitcnt vmcnt(1)
	v_ashrrev_i32_e32 v24, 4, v2
	v_lshrrev_b32_e32 v5, 2, v176
	s_waitcnt vmcnt(0)
	v_add_u32_e32 v29, 0, v0
	v_lshl_add_u32 v28, v24, 8, 0
	v_lshlrev_b32_e32 v4, 1, v24
	s_movk_i32 s6, 0xff02
	v_and_b32_e32 v18, 12, v5
	v_mad_u64_u32 v[2:3], s[4:5], v24, s6, v[28:29]
	v_xor_b32_e32 v5, 0x50, v4
	v_xad_u32 v3, v4, 16, 0
	v_xad_u32 v49, v4, 32, 0
	v_xad_u32 v50, v4, 48, 0
	v_xad_u32 v51, v4, 64, 0
	v_add_u32_e32 v52, 0, v5
	v_xor_b32_e32 v5, 0x60, v4
	v_xor_b32_e32 v4, 0x70, v4
	v_add_u32_e32 v54, 0, v4
	v_add_u32_e32 v4, 0x400, v176
	v_ashrrev_i32_e32 v30, 4, v4
	v_lshl_add_u32 v34, v30, 8, 0
	v_lshlrev_b32_e32 v6, 1, v30
	v_add_u32_e32 v53, 0, v5
	v_mad_u64_u32 v[4:5], s[4:5], v30, s6, v[34:35]
	v_xor_b32_e32 v7, 0x50, v6
	v_xad_u32 v5, v6, 16, 0
	v_xad_u32 v55, v6, 32, 0
	v_xad_u32 v56, v6, 48, 0
	v_xad_u32 v57, v6, 64, 0
	v_add_u32_e32 v58, 0, v7
	v_xor_b32_e32 v7, 0x60, v6
	v_xor_b32_e32 v6, 0x70, v6
	v_add_u32_e32 v60, 0, v6
	v_add_u32_e32 v6, 0x600, v176
	v_ashrrev_i32_e32 v36, 4, v6
	v_lshl_add_u32 v40, v36, 8, 0
	v_add_u32_e32 v59, 0, v7
	v_lshlrev_b32_e32 v61, 1, v36
	v_mad_u64_u32 v[6:7], s[4:5], v36, s6, v[40:41]
	s_load_dwordx2 s[6:7], s[2:3], 0x98
	v_ashrrev_i32_e32 v20, 4, v176
	v_xor_b32_e32 v67, 0x50, v61
	v_lshlrev_b32_e32 v0, 3, v1
	v_lshlrev_b32_e32 v65, 1, v20
	v_lshlrev_b32_e32 v1, 11, v1
	v_xad_u32 v7, v61, 16, 0
	v_xad_u32 v62, v61, 32, 0
	v_xad_u32 v63, v61, 48, 0
	v_xad_u32 v95, v61, 64, 0
	v_add_u32_e32 v96, 0, v67
	v_xor_b32_e32 v67, 0x60, v61
	v_xor_b32_e32 v61, 0x70, v61
	v_add_u32_e32 v9, 0, v19
	v_add_u32_e32 v10, 0, v35
	v_add_u32_e32 v11, 0, v41
	v_add_u32_e32 v12, 0, v43
	v_lshlrev_b32_e32 v22, 7, v20
	v_lshlrev_b32_e32 v13, 8, v20
	v_add_u32_e32 v14, 0, v64
	v_add_u32_e32 v66, 0, v1
	v_xor_b32_e32 v15, 16, v65
	v_xor_b32_e32 v42, 32, v65
	v_xor_b32_e32 v44, 48, v65
	v_xor_b32_e32 v45, 64, v65
	v_xor_b32_e32 v46, 0x50, v65
	v_xor_b32_e32 v47, 0x60, v65
	v_xor_b32_e32 v48, 0x70, v65
	v_lshlrev_b32_e32 v26, 7, v24
	v_lshlrev_b32_e32 v32, 7, v30
	v_lshlrev_b32_e32 v38, 7, v36
	v_add_u32_e32 v97, 0, v67
	v_add_u32_e32 v61, 0, v61
	v_readlane_b32 s2, v254, 41
	v_ashrrev_i32_e32 v17, 31, v16
	v_ashrrev_i32_e32 v23, 31, v22
	v_ashrrev_i32_e32 v21, 31, v20
	v_ashrrev_i32_e32 v27, 31, v26
	v_ashrrev_i32_e32 v25, 31, v24
	v_ashrrev_i32_e32 v33, 31, v32
	v_ashrrev_i32_e32 v31, 31, v30
	v_ashrrev_i32_e32 v39, 31, v38
	v_ashrrev_i32_e32 v37, 31, v36
	v_lshlrev_b32_e32 v192, 1, v0
	v_add_u32_e32 v67, v14, v13
	v_add_u32_e32 v68, v66, v15
	v_add_u32_e32 v69, v66, v42
	v_add_u32_e32 v70, v66, v44
	v_add_u32_e32 v71, v66, v45
	v_add_u32_e32 v72, v66, v46
	v_add_u32_e32 v73, v66, v47
	v_add_u32_e32 v74, v66, v48
	v_add_u32_e32 v75, v2, v1
	v_add_u32_e32 v76, v3, v1
	v_add_u32_e32 v77, v49, v1
	v_add_u32_e32 v78, v50, v1
	v_add_u32_e32 v79, v51, v1
	v_add_u32_e32 v80, v52, v1
	v_add_u32_e32 v81, v53, v1
	v_add_u32_e32 v82, v54, v1
	v_add_u32_e32 v83, v4, v1
	v_add_u32_e32 v84, v5, v1
	v_add_u32_e32 v85, v55, v1
	v_add_u32_e32 v86, v56, v1
	v_add_u32_e32 v87, v57, v1
	v_add_u32_e32 v88, v58, v1
	v_add_u32_e32 v89, v59, v1
	v_add_u32_e32 v90, v60, v1
	v_add_u32_e32 v91, v6, v1
	v_add_u32_e32 v92, v7, v1
	v_add_u32_e32 v93, v62, v1
	v_add_u32_e32 v94, v63, v1
	v_add_u32_e32 v95, v95, v1
	v_add_u32_e32 v96, v96, v1
	v_add_u32_e32 v97, v97, v1
	v_add_u32_e32 v98, v61, v1
	v_add_u32_e32 v99, v9, v8
	v_add_u32_e32 v100, v10, v8
	v_add_u32_e32 v101, v11, v8
	v_add_u32_e32 v102, v12, v8
	s_mov_b32 s14, s2
	s_mov_b32 s20, 0x3d372713
	s_mov_b32 s22, 0x3f4c422a
	v_readlane_b32 s3, v254, 42
	v_and_b32_e32 v154, 15, v176
	v_lshlrev_b32_e32 v154, 4, v154
	v_xor_b32_e32 v65, v154, v65
	v_xor_b32_e32 v68, v154, v68
	v_xor_b32_e32 v69, v154, v69
	v_xor_b32_e32 v70, v154, v70
	v_xor_b32_e32 v71, v154, v71
	v_xor_b32_e32 v72, v154, v72
	v_xor_b32_e32 v73, v154, v73
	v_xor_b32_e32 v74, v154, v74
	v_xor_b32_e32 v75, v154, v75
	v_xor_b32_e32 v76, v154, v76
	v_xor_b32_e32 v77, v154, v77
	v_xor_b32_e32 v78, v154, v78
	v_xor_b32_e32 v79, v154, v79
	v_xor_b32_e32 v80, v154, v80
	v_xor_b32_e32 v81, v154, v81
	v_xor_b32_e32 v82, v154, v82
	v_xor_b32_e32 v83, v154, v83
	v_xor_b32_e32 v84, v154, v84
	v_xor_b32_e32 v85, v154, v85
	v_xor_b32_e32 v86, v154, v86
	v_xor_b32_e32 v87, v154, v87
	v_xor_b32_e32 v88, v154, v88
	v_xor_b32_e32 v89, v154, v89
	v_xor_b32_e32 v90, v154, v90
	v_xor_b32_e32 v91, v154, v91
	v_xor_b32_e32 v92, v154, v92
	v_xor_b32_e32 v93, v154, v93
	v_xor_b32_e32 v94, v154, v94
	v_xor_b32_e32 v95, v154, v95
	v_xor_b32_e32 v96, v154, v96
	v_xor_b32_e32 v97, v154, v97
	v_xor_b32_e32 v98, v154, v98
	v_bfe_u32 v155, v176, 3, 1
	v_lshlrev_b32_e32 v155, 4, v155
	v_xor_b32_e32 v99, v155, v99
	v_xor_b32_e32 v100, v155, v100
	v_xor_b32_e32 v101, v155, v101
	v_xor_b32_e32 v102, v155, v102
	v_xor_b32_e32 v156, 0x20, v99
	v_xor_b32_e32 v157, 0x20, v100
	v_xor_b32_e32 v158, 0x20, v101
	v_xor_b32_e32 v159, 0x20, v102
	v_xor_b32_e32 v160, 0x40, v99
	v_xor_b32_e32 v161, 0x40, v100
	v_xor_b32_e32 v162, 0x40, v101
	v_xor_b32_e32 v163, 0x40, v102
	v_xor_b32_e32 v164, 0x60, v99
	v_xor_b32_e32 v165, 0x60, v100
	v_xor_b32_e32 v166, 0x60, v101
	v_xor_b32_e32 v167, 0x60, v102
	v_xor_b32_e32 v168, 0x80, v99
	v_xor_b32_e32 v169, 0x80, v100
	v_xor_b32_e32 v170, 0x80, v101
	v_xor_b32_e32 v171, 0x80, v102
	v_xor_b32_e32 v172, 0xa0, v99
	v_xor_b32_e32 v173, 0xa0, v100
	v_xor_b32_e32 v174, 0xa0, v101
	v_xor_b32_e32 v175, 0xa0, v102
	v_xor_b32_e32 v176, 0xc0, v99
	v_xor_b32_e32 v177, 0xc0, v100
	v_xor_b32_e32 v178, 0xc0, v101
	v_xor_b32_e32 v179, 0xc0, v102
	v_xor_b32_e32 v180, 0xe0, v99
	v_xor_b32_e32 v181, 0xe0, v100
	v_xor_b32_e32 v182, 0xe0, v101
	v_xor_b32_e32 v183, 0xe0, v102
	s_nop 0
	s_nop 0
	s_nop 0
	s_nop 0
	s_nop 0
	s_nop 0
	s_nop 0

.Lcvt_wdone2:
	s_waitcnt lgkmcnt(0)
	s_barrier
	ds_read2_b32 v[0:1], v19 offset1:65
	ds_read2_b32 v[22:23], v19 offset0:130 offset1:195
	v_add_u32_e32 v20, 0x400, v19
	ds_read2_b32 v[24:25], v20 offset0:4 offset1:69
	ds_read2_b32 v[26:27], v20 offset0:134 offset1:199
	s_waitcnt lgkmcnt(3)
	v_cvt_pk_bf16_f32 v20, v0, v1
	s_waitcnt lgkmcnt(2)
	v_cvt_pk_bf16_f32 v21, v22, v23
	s_waitcnt lgkmcnt(1)
	v_cvt_pk_bf16_f32 v22, v24, v25
	s_waitcnt lgkmcnt(0)
	v_cvt_pk_bf16_f32 v23, v26, v27
	global_store_dwordx4 v[146:147], v[20:23], off
	s_branch .LBB0_488
	s_nop 0
	s_nop 0
	s_nop 0
	s_nop 0
	s_nop 0
	s_nop 0
	s_nop 0
	s_nop 0
	s_nop 0
.LBB0_486:
	s_mov_b64 s[6:7], 0x600000
	s_movk_i32 s23, 0x1600
	s_mov_b64 s[8:9], 0x1600
	s_cbranch_execz .LBB0_464
	s_branch .LBB0_465
